# P0 weight transposes: all 32 row loads of an item in flight before the first wait (counted vmcnt), on top of attention changes + prio S1
# speedup vs baseline: 1.0164x; 1.0015x over previous
; DI unsigned pk2(float lo, float hi) { f32x2_t v = {lo, hi}; bf16x2_t b = __builtin_convertvector(v, bf16x2_t); return __builtin_bit_cast(unsigned, b); }
; DI void p0_transpose_item(const float* W, int K, int N, bf16_t* WT, float* scr, int item, int lane) {
;     const int nblk = N / 32, kb = item / nblk, nb = item % nblk, k0 = 64 * kb, n0 = 32 * nb;
; #pragma unroll 8
;     for (int i = 0; i < 32; ++i) { const int kk = 2 * i + (lane >> 5); scr[kk * 33 + (lane & 31)] = __builtin_nontemporal_load(W + (size_t)(k0 + kk) * N + n0 + (lane & 31)); }
;     asm volatile("s_waitcnt vmcnt(0) lgkmcnt(0)" ::: "memory");
;     const int c = lane & 7;
; #pragma unroll
;     for (int j = 0; j < 4; ++j) {
;         const int n = (lane >> 3) + 8 * j; const float* s = scr + (8 * c) * 33 + n;
;         u32x4 o; o.x = pk2(s[0], s[33]); o.y = pk2(s[66], s[99]); o.z = pk2(s[132], s[165]); o.w = pk2(s[198], s[231]);
;         *(u32x4*)(WT + (size_t)(n0 + n) * K + k0 + 8 * c) = o;
;     }
;     asm volatile("s_waitcnt lgkmcnt(0)" ::: "memory");
; }
.LBB0_8:
	v_lshl_add_u64 v[42:43], v[26:27], 0, s[4:5]
	v_lshl_add_u64 v[44:45], v[24:25], 0, s[4:5]
	v_lshl_add_u64 v[46:47], v[22:23], 0, s[4:5]
	v_lshl_add_u64 v[48:49], v[20:21], 0, s[4:5]
	v_lshl_add_u64 v[50:51], v[18:19], 0, s[4:5]
	v_lshl_add_u64 v[52:53], v[16:17], 0, s[4:5]
	v_lshl_add_u64 v[54:55], v[14:15], 0, s[4:5]
	v_lshl_add_u64 v[56:57], v[12:13], 0, s[4:5]
	global_load_dword v58, v[42:43], off nt
	global_load_dword v59, v[44:45], off nt
	global_load_dword v60, v[46:47], off nt
	global_load_dword v61, v[48:49], off nt
	global_load_dword v62, v[50:51], off nt
	global_load_dword v63, v[52:53], off nt
	global_load_dword v64, v[54:55], off nt
	global_load_dword v65, v[56:57], off nt
	s_add_u32 s4, s4, 0x20000
	s_addc_u32 s5, s5, 0
	v_lshl_add_u64 v[42:43], v[26:27], 0, s[4:5]
	v_lshl_add_u64 v[44:45], v[24:25], 0, s[4:5]
	v_lshl_add_u64 v[46:47], v[22:23], 0, s[4:5]
	v_lshl_add_u64 v[48:49], v[20:21], 0, s[4:5]
	v_lshl_add_u64 v[50:51], v[18:19], 0, s[4:5]
	v_lshl_add_u64 v[52:53], v[16:17], 0, s[4:5]
	v_lshl_add_u64 v[54:55], v[14:15], 0, s[4:5]
	v_lshl_add_u64 v[56:57], v[12:13], 0, s[4:5]
	global_load_dword v66, v[42:43], off nt
	global_load_dword v67, v[44:45], off nt
	global_load_dword v68, v[46:47], off nt
	global_load_dword v69, v[48:49], off nt
	global_load_dword v70, v[50:51], off nt
	global_load_dword v71, v[52:53], off nt
	global_load_dword v72, v[54:55], off nt
	global_load_dword v73, v[56:57], off nt
	s_add_u32 s4, s4, 0x20000
	s_addc_u32 s5, s5, 0
	v_lshl_add_u64 v[42:43], v[26:27], 0, s[4:5]
	v_lshl_add_u64 v[44:45], v[24:25], 0, s[4:5]
	v_lshl_add_u64 v[46:47], v[22:23], 0, s[4:5]
	v_lshl_add_u64 v[48:49], v[20:21], 0, s[4:5]
	v_lshl_add_u64 v[50:51], v[18:19], 0, s[4:5]
	v_lshl_add_u64 v[52:53], v[16:17], 0, s[4:5]
	v_lshl_add_u64 v[54:55], v[14:15], 0, s[4:5]
	v_lshl_add_u64 v[56:57], v[12:13], 0, s[4:5]
	global_load_dword v74, v[42:43], off nt
	global_load_dword v75, v[44:45], off nt
	global_load_dword v76, v[46:47], off nt
	global_load_dword v77, v[48:49], off nt
	global_load_dword v78, v[50:51], off nt
	global_load_dword v79, v[52:53], off nt
	global_load_dword v80, v[54:55], off nt
	global_load_dword v81, v[56:57], off nt
	s_add_u32 s4, s4, 0x20000
	s_addc_u32 s5, s5, 0
	v_lshl_add_u64 v[42:43], v[26:27], 0, s[4:5]
	v_lshl_add_u64 v[44:45], v[24:25], 0, s[4:5]
	v_lshl_add_u64 v[46:47], v[22:23], 0, s[4:5]
	v_lshl_add_u64 v[48:49], v[20:21], 0, s[4:5]
	v_lshl_add_u64 v[50:51], v[18:19], 0, s[4:5]
	v_lshl_add_u64 v[52:53], v[16:17], 0, s[4:5]
	v_lshl_add_u64 v[54:55], v[14:15], 0, s[4:5]
	v_lshl_add_u64 v[56:57], v[12:13], 0, s[4:5]
	global_load_dword v82, v[42:43], off nt
	global_load_dword v83, v[44:45], off nt
	global_load_dword v84, v[46:47], off nt
	global_load_dword v85, v[48:49], off nt
	global_load_dword v86, v[50:51], off nt
	global_load_dword v87, v[52:53], off nt
	global_load_dword v88, v[54:55], off nt
	global_load_dword v89, v[56:57], off nt
	v_add_u32_e32 v42, 0x400, v2
	s_waitcnt vmcnt(30)
	ds_write2_b32 v2, v58, v59 offset1:66
	s_waitcnt vmcnt(28)
	ds_write2_b32 v2, v60, v61 offset0:132 offset1:198
	s_waitcnt vmcnt(26)
	ds_write2_b32 v42, v62, v63 offset0:8 offset1:74
	s_waitcnt vmcnt(24)
	ds_write2_b32 v42, v64, v65 offset0:140 offset1:206
	v_add_u32_e32 v2, 0x840, v2
	v_add_u32_e32 v42, 0x400, v2
	s_waitcnt vmcnt(22)
	ds_write2_b32 v2, v66, v67 offset1:66
	s_waitcnt vmcnt(20)
	ds_write2_b32 v2, v68, v69 offset0:132 offset1:198
	s_waitcnt vmcnt(18)
	ds_write2_b32 v42, v70, v71 offset0:8 offset1:74
	s_waitcnt vmcnt(16)
	ds_write2_b32 v42, v72, v73 offset0:140 offset1:206
	v_add_u32_e32 v2, 0x840, v2
	v_add_u32_e32 v42, 0x400, v2
	s_waitcnt vmcnt(14)
	ds_write2_b32 v2, v74, v75 offset1:66
	s_waitcnt vmcnt(12)
	ds_write2_b32 v2, v76, v77 offset0:132 offset1:198
	s_waitcnt vmcnt(10)
	ds_write2_b32 v42, v78, v79 offset0:8 offset1:74
	s_waitcnt vmcnt(8)
	ds_write2_b32 v42, v80, v81 offset0:140 offset1:206
	v_add_u32_e32 v2, 0x840, v2
	v_add_u32_e32 v42, 0x400, v2
	s_waitcnt vmcnt(6)
	ds_write2_b32 v2, v82, v83 offset1:66
	s_waitcnt vmcnt(4)
	ds_write2_b32 v2, v84, v85 offset0:132 offset1:198
	s_waitcnt vmcnt(2)
	ds_write2_b32 v42, v86, v87 offset0:8 offset1:74
	s_waitcnt vmcnt(0)
	ds_write2_b32 v42, v88, v89 offset0:140 offset1:206
	v_add_u32_e32 v2, 0x840, v2
	s_waitcnt vmcnt(0) lgkmcnt(0)
	ds_read2_b32 v[16:17], v30 offset0:33 offset1:41
	ds_read2_b32 v[18:19], v30 offset1:8
	ds_read2_b32 v[20:21], v30 offset0:66 offset1:74
	ds_read2_b32 v[22:23], v30 offset0:99 offset1:107
	ds_read2_b32 v[24:25], v30 offset0:132 offset1:140
	ds_read2_b32 v[26:27], v30 offset0:165 offset1:173
	ds_read2_b32 v[42:43], v30 offset0:198 offset1:206
	ds_read2_b32 v[44:45], v30 offset0:231 offset1:239
	s_add_i32 s0, s50, 0xe400
	s_lshl_b32 s4, s50, 5
	s_and_b32 s0, s0, 0xffc0
	s_and_b32 s4, s4, 0x7e0
	s_lshl_b32 s0, s0, 1
	v_or_b32_e32 v2, s4, v29
	v_lshl_add_u64 v[46:47], v[4:5], 0, s[0:1]
	v_lshlrev_b32_e32 v2, 12, v2
	s_waitcnt lgkmcnt(6)
	v_cvt_pk_bf16_f32 v12, v18, v16
	s_waitcnt lgkmcnt(4)
	v_cvt_pk_bf16_f32 v13, v20, v22
	s_waitcnt lgkmcnt(2)
	v_cvt_pk_bf16_f32 v14, v24, v26
	s_waitcnt lgkmcnt(0)
	v_cvt_pk_bf16_f32 v15, v42, v44
	v_lshl_add_u64 v[48:49], v[46:47], 0, v[2:3]
	global_store_dwordx4 v[48:49], v[12:15], off
	v_or_b32_e32 v2, s4, v31
	v_lshlrev_b32_e32 v2, 12, v2
	v_cvt_pk_bf16_f32 v12, v19, v17
	v_cvt_pk_bf16_f32 v13, v21, v23
	v_cvt_pk_bf16_f32 v14, v25, v27
	v_cvt_pk_bf16_f32 v15, v43, v45
	ds_read2_b32 v[18:19], v30 offset0:49 offset1:57
	ds_read2_b32 v[20:21], v30 offset0:16 offset1:24
	ds_read2_b32 v[22:23], v30 offset0:82 offset1:90
	ds_read2_b32 v[24:25], v30 offset0:115 offset1:123
	ds_read2_b32 v[26:27], v30 offset0:148 offset1:156
	ds_read2_b32 v[42:43], v30 offset0:181 offset1:189
	ds_read2_b32 v[44:45], v30 offset0:214 offset1:222
	ds_read2_b32 v[48:49], v30 offset0:247 offset1:255
	v_lshl_add_u64 v[16:17], v[46:47], 0, v[2:3]
	v_or_b32_e32 v2, s4, v32
	v_lshlrev_b32_e32 v2, 12, v2
	global_store_dwordx4 v[16:17], v[12:15], off
	v_lshl_add_u64 v[16:17], v[46:47], 0, v[2:3]
	v_or_b32_e32 v2, s4, v33
	s_waitcnt lgkmcnt(6)
	v_cvt_pk_bf16_f32 v12, v20, v18
	s_waitcnt lgkmcnt(4)
	v_cvt_pk_bf16_f32 v13, v22, v24
	s_waitcnt lgkmcnt(2)
	v_cvt_pk_bf16_f32 v14, v26, v42
	s_waitcnt lgkmcnt(0)
	v_cvt_pk_bf16_f32 v15, v44, v48
	v_lshlrev_b32_e32 v2, 12, v2
	global_store_dwordx4 v[16:17], v[12:15], off
	v_lshl_add_u64 v[16:17], v[46:47], 0, v[2:3]
	s_mov_b64 s[4:5], 0
	v_cvt_pk_bf16_f32 v12, v21, v19
	v_cvt_pk_bf16_f32 v13, v23, v25
	v_cvt_pk_bf16_f32 v14, v27, v43
	v_cvt_pk_bf16_f32 v15, v45, v49
	global_store_dwordx4 v[16:17], v[12:15], off
	s_waitcnt lgkmcnt(0)

; DI unsigned pk2(float lo, float hi) { f32x2_t v = {lo, hi}; bf16x2_t b = __builtin_convertvector(v, bf16x2_t); return __builtin_bit_cast(unsigned, b); }
; DI void p0_transpose_item(const float* W, int K, int N, bf16_t* WT, float* scr, int item, int lane) {
;     const int nblk = N / 32, kb = item / nblk, nb = item % nblk, k0 = 64 * kb, n0 = 32 * nb;
; #pragma unroll 8
;     for (int i = 0; i < 32; ++i) { const int kk = 2 * i + (lane >> 5); scr[kk * 33 + (lane & 31)] = __builtin_nontemporal_load(W + (size_t)(k0 + kk) * N + n0 + (lane & 31)); }
;     asm volatile("s_waitcnt vmcnt(0) lgkmcnt(0)" ::: "memory");
;     const int c = lane & 7;
; #pragma unroll
;     for (int j = 0; j < 4; ++j) {
;         const int n = (lane >> 3) + 8 * j; const float* s = scr + (8 * c) * 33 + n;
;         u32x4 o; o.x = pk2(s[0], s[33]); o.y = pk2(s[66], s[99]); o.z = pk2(s[132], s[165]); o.w = pk2(s[198], s[231]);
;         *(u32x4*)(WT + (size_t)(n0 + n) * K + k0 + 8 * c) = o;
;     }
;     asm volatile("s_waitcnt lgkmcnt(0)" ::: "memory");
; }
.LBB0_12:
	v_lshl_add_u64 v[42:43], v[26:27], 0, s[8:9]
	v_lshl_add_u64 v[44:45], v[24:25], 0, s[8:9]
	v_lshl_add_u64 v[46:47], v[22:23], 0, s[8:9]
	v_lshl_add_u64 v[48:49], v[20:21], 0, s[8:9]
	v_lshl_add_u64 v[50:51], v[18:19], 0, s[8:9]
	v_lshl_add_u64 v[52:53], v[16:17], 0, s[8:9]
	v_lshl_add_u64 v[54:55], v[14:15], 0, s[8:9]
	v_lshl_add_u64 v[56:57], v[12:13], 0, s[8:9]
	global_load_dword v58, v[42:43], off nt
	global_load_dword v59, v[44:45], off nt
	global_load_dword v60, v[46:47], off nt
	global_load_dword v61, v[48:49], off nt
	global_load_dword v62, v[50:51], off nt
	global_load_dword v63, v[52:53], off nt
	global_load_dword v64, v[54:55], off nt
	global_load_dword v65, v[56:57], off nt
	s_add_u32 s8, s8, 0x70000
	s_addc_u32 s9, s9, 0
	v_lshl_add_u64 v[42:43], v[26:27], 0, s[8:9]
	v_lshl_add_u64 v[44:45], v[24:25], 0, s[8:9]
	v_lshl_add_u64 v[46:47], v[22:23], 0, s[8:9]
	v_lshl_add_u64 v[48:49], v[20:21], 0, s[8:9]
	v_lshl_add_u64 v[50:51], v[18:19], 0, s[8:9]
	v_lshl_add_u64 v[52:53], v[16:17], 0, s[8:9]
	v_lshl_add_u64 v[54:55], v[14:15], 0, s[8:9]
	v_lshl_add_u64 v[56:57], v[12:13], 0, s[8:9]
	global_load_dword v66, v[42:43], off nt
	global_load_dword v67, v[44:45], off nt
	global_load_dword v68, v[46:47], off nt
	global_load_dword v69, v[48:49], off nt
	global_load_dword v70, v[50:51], off nt
	global_load_dword v71, v[52:53], off nt
	global_load_dword v72, v[54:55], off nt
	global_load_dword v73, v[56:57], off nt
	s_add_u32 s8, s8, 0x70000
	s_addc_u32 s9, s9, 0
	v_lshl_add_u64 v[42:43], v[26:27], 0, s[8:9]
	v_lshl_add_u64 v[44:45], v[24:25], 0, s[8:9]
	v_lshl_add_u64 v[46:47], v[22:23], 0, s[8:9]
	v_lshl_add_u64 v[48:49], v[20:21], 0, s[8:9]
	v_lshl_add_u64 v[50:51], v[18:19], 0, s[8:9]
	v_lshl_add_u64 v[52:53], v[16:17], 0, s[8:9]
	v_lshl_add_u64 v[54:55], v[14:15], 0, s[8:9]
	v_lshl_add_u64 v[56:57], v[12:13], 0, s[8:9]
	global_load_dword v74, v[42:43], off nt
	global_load_dword v75, v[44:45], off nt
	global_load_dword v76, v[46:47], off nt
	global_load_dword v77, v[48:49], off nt
	global_load_dword v78, v[50:51], off nt
	global_load_dword v79, v[52:53], off nt
	global_load_dword v80, v[54:55], off nt
	global_load_dword v81, v[56:57], off nt
	s_add_u32 s8, s8, 0x70000
	s_addc_u32 s9, s9, 0
	v_lshl_add_u64 v[42:43], v[26:27], 0, s[8:9]
	v_lshl_add_u64 v[44:45], v[24:25], 0, s[8:9]
	v_lshl_add_u64 v[46:47], v[22:23], 0, s[8:9]
	v_lshl_add_u64 v[48:49], v[20:21], 0, s[8:9]
	v_lshl_add_u64 v[50:51], v[18:19], 0, s[8:9]
	v_lshl_add_u64 v[52:53], v[16:17], 0, s[8:9]
	v_lshl_add_u64 v[54:55], v[14:15], 0, s[8:9]
	v_lshl_add_u64 v[56:57], v[12:13], 0, s[8:9]
	global_load_dword v82, v[42:43], off nt
	global_load_dword v83, v[44:45], off nt
	global_load_dword v84, v[46:47], off nt
	global_load_dword v85, v[48:49], off nt
	global_load_dword v86, v[50:51], off nt
	global_load_dword v87, v[52:53], off nt
	global_load_dword v88, v[54:55], off nt
	global_load_dword v89, v[56:57], off nt
	v_add_u32_e32 v42, 0x400, v2
	s_waitcnt vmcnt(30)
	ds_write2_b32 v2, v58, v59 offset1:66
	s_waitcnt vmcnt(28)
	ds_write2_b32 v2, v60, v61 offset0:132 offset1:198
	s_waitcnt vmcnt(26)
	ds_write2_b32 v42, v62, v63 offset0:8 offset1:74
	s_waitcnt vmcnt(24)
	ds_write2_b32 v42, v64, v65 offset0:140 offset1:206
	v_add_u32_e32 v2, 0x840, v2
	v_add_u32_e32 v42, 0x400, v2
	s_waitcnt vmcnt(22)
	ds_write2_b32 v2, v66, v67 offset1:66
	s_waitcnt vmcnt(20)
	ds_write2_b32 v2, v68, v69 offset0:132 offset1:198
	s_waitcnt vmcnt(18)
	ds_write2_b32 v42, v70, v71 offset0:8 offset1:74
	s_waitcnt vmcnt(16)
	ds_write2_b32 v42, v72, v73 offset0:140 offset1:206
	v_add_u32_e32 v2, 0x840, v2
	v_add_u32_e32 v42, 0x400, v2
	s_waitcnt vmcnt(14)
	ds_write2_b32 v2, v74, v75 offset1:66
	s_waitcnt vmcnt(12)
	ds_write2_b32 v2, v76, v77 offset0:132 offset1:198
	s_waitcnt vmcnt(10)
	ds_write2_b32 v42, v78, v79 offset0:8 offset1:74
	s_waitcnt vmcnt(8)
	ds_write2_b32 v42, v80, v81 offset0:140 offset1:206
	v_add_u32_e32 v2, 0x840, v2
	v_add_u32_e32 v42, 0x400, v2
	s_waitcnt vmcnt(6)
	ds_write2_b32 v2, v82, v83 offset1:66
	s_waitcnt vmcnt(4)
	ds_write2_b32 v2, v84, v85 offset0:132 offset1:198
	s_waitcnt vmcnt(2)
	ds_write2_b32 v42, v86, v87 offset0:8 offset1:74
	s_waitcnt vmcnt(0)
	ds_write2_b32 v42, v88, v89 offset0:140 offset1:206
	v_add_u32_e32 v2, 0x840, v2
	s_waitcnt vmcnt(0) lgkmcnt(0)
	ds_read2_b32 v[16:17], v30 offset0:33 offset1:41
	ds_read2_b32 v[18:19], v30 offset1:8
	ds_read2_b32 v[20:21], v30 offset0:66 offset1:74
	ds_read2_b32 v[22:23], v30 offset0:99 offset1:107
	ds_read2_b32 v[24:25], v30 offset0:132 offset1:140
	ds_read2_b32 v[26:27], v30 offset0:165 offset1:173
	ds_read2_b32 v[42:43], v30 offset0:198 offset1:206
	ds_read2_b32 v[44:45], v30 offset0:231 offset1:239
	v_or_b32_e32 v48, s4, v29
	s_ashr_i32 s7, s6, 31
	v_ashrrev_i32_e32 v49, 31, v48
	v_lshl_add_u64 v[46:47], s[6:7], 1, v[6:7]
	v_lshlrev_b64 v[48:49], 12, v[48:49]
	s_waitcnt lgkmcnt(6)
	v_cvt_pk_bf16_f32 v12, v18, v16
	s_waitcnt lgkmcnt(4)
	v_cvt_pk_bf16_f32 v13, v20, v22
	s_waitcnt lgkmcnt(2)
	v_cvt_pk_bf16_f32 v14, v24, v26
	s_waitcnt lgkmcnt(0)
	v_cvt_pk_bf16_f32 v15, v42, v44
	v_lshl_add_u64 v[48:49], v[46:47], 0, v[48:49]
	v_or_b32_e32 v16, s4, v31
	global_store_dwordx4 v[48:49], v[12:15], off
	s_nop 1
	v_cvt_pk_bf16_f32 v12, v19, v17
	v_ashrrev_i32_e32 v17, 31, v16
	v_cvt_pk_bf16_f32 v13, v21, v23
	v_cvt_pk_bf16_f32 v14, v25, v27
	v_cvt_pk_bf16_f32 v15, v43, v45
	v_lshlrev_b64 v[16:17], 12, v[16:17]
	ds_read2_b32 v[18:19], v30 offset0:49 offset1:57
	ds_read2_b32 v[20:21], v30 offset0:16 offset1:24
	ds_read2_b32 v[22:23], v30 offset0:82 offset1:90
	ds_read2_b32 v[24:25], v30 offset0:115 offset1:123
	ds_read2_b32 v[26:27], v30 offset0:148 offset1:156
	ds_read2_b32 v[42:43], v30 offset0:181 offset1:189
	ds_read2_b32 v[44:45], v30 offset0:214 offset1:222
	ds_read2_b32 v[48:49], v30 offset0:247 offset1:255
	v_lshl_add_u64 v[16:17], v[46:47], 0, v[16:17]
	global_store_dwordx4 v[16:17], v[12:15], off
	v_or_b32_e32 v16, s4, v32
	v_ashrrev_i32_e32 v17, 31, v16
	v_lshlrev_b64 v[16:17], 12, v[16:17]
	s_waitcnt lgkmcnt(6)
	v_cvt_pk_bf16_f32 v12, v20, v18
	s_waitcnt lgkmcnt(4)
	v_cvt_pk_bf16_f32 v13, v22, v24
	s_waitcnt lgkmcnt(2)
	v_cvt_pk_bf16_f32 v14, v26, v42
	s_waitcnt lgkmcnt(0)
	v_cvt_pk_bf16_f32 v15, v44, v48
	v_lshl_add_u64 v[16:17], v[46:47], 0, v[16:17]
	global_store_dwordx4 v[16:17], v[12:15], off
	v_or_b32_e32 v16, s4, v33
	v_ashrrev_i32_e32 v17, 31, v16
	v_lshlrev_b64 v[16:17], 12, v[16:17]
	v_cvt_pk_bf16_f32 v12, v21, v19
	v_cvt_pk_bf16_f32 v13, v23, v25
	v_cvt_pk_bf16_f32 v14, v27, v43
	v_cvt_pk_bf16_f32 v15, v45, v49
	v_lshl_add_u64 v[16:17], v[46:47], 0, v[16:17]
	global_store_dwordx4 v[16:17], v[12:15], off
	s_waitcnt lgkmcnt(0)
	s_branch .LBB0_5
